# GEMM main loop (first instantiation): per-phase s_setprio flips removed
# baseline (speedup 1.0000x reference)
.LBB0_77:
	s_add_i32 s98, s34, 2
	s_add_u32 s50, s8, 0x80
	s_addc_u32 s35, s9, 0
	s_add_i32 s99, 0, 0x10000
	s_cmp_eq_u32 s5, s34
	s_cselect_b32 s35, s19, s35
	s_cselect_b32 s34, s18, s50
	s_cselect_b32 s51, s21, s73
	s_cselect_b32 s50, s20, s42
	s_add_i32 vcc_lo, 0, 0x14000
	v_add_u32_e32 v164, s99, v143
	v_add_u32_e32 v178, vcc_lo, v143
	ds_read_b128 v[130:133], v164
	ds_read_b128 v[156:159], v164 offset:1024
	ds_read_b128 v[160:163], v164 offset:2048
	ds_read_b128 v[164:167], v164 offset:3072
	ds_read_b128 v[168:171], v178
	ds_read_b128 v[172:175], v178 offset:1024
	ds_read_b128 v[184:187], v178 offset:2048
	ds_read_b128 v[188:191], v178 offset:3072
	v_lshl_add_u64 v[178:179], s[8:9], 0, v[152:153]
	s_add_i32 m0, s11, 0xc000
	ds_read_b128 v[192:195], v149
	ds_read_b128 v[196:199], v149 offset:1024
	ds_read_b128 v[200:203], v149 offset:2048
	ds_read_b128 v[204:207], v149 offset:3072
	ds_read_b128 v[208:211], v149 offset:4096
	ds_read_b128 v[212:215], v149 offset:5120
	ds_read_b128 v[216:219], v149 offset:6144
	ds_read_b128 v[220:223], v149 offset:7168
	global_load_lds_dwordx4 v[178:179], off
	v_lshl_add_u64 v[178:179], s[8:9], 0, v[154:155]
	s_add_i32 m0, s11, 0xe000
	s_nop 0
	global_load_lds_dwordx4 v[178:179], off
	s_waitcnt vmcnt(8)
	s_waitcnt lgkmcnt(0)
	s_barrier
	s_waitcnt lgkmcnt(0)
	v_mfma_f32_16x16x32_bf16 v[126:129], v[130:133], v[192:195], v[126:129]
	v_mfma_f32_16x16x32_bf16 v[122:125], v[160:163], v[192:195], v[122:125]
	v_mfma_f32_16x16x32_bf16 v[110:113], v[130:133], v[200:203], v[110:113]
	v_mfma_f32_16x16x32_bf16 v[106:109], v[160:163], v[200:203], v[106:109]
	v_mfma_f32_16x16x32_bf16 v[94:97], v[130:133], v[208:211], v[94:97]
	v_mfma_f32_16x16x32_bf16 v[90:93], v[160:163], v[208:211], v[90:93]
	v_mfma_f32_16x16x32_bf16 v[78:81], v[130:133], v[216:219], v[78:81]
	v_mfma_f32_16x16x32_bf16 v[74:77], v[160:163], v[216:219], v[74:77]
	v_mfma_f32_16x16x32_bf16 v[126:129], v[156:159], v[196:199], v[126:129]
	v_mfma_f32_16x16x32_bf16 v[122:125], v[164:167], v[196:199], v[122:125]
	v_mfma_f32_16x16x32_bf16 v[110:113], v[156:159], v[204:207], v[110:113]
	v_mfma_f32_16x16x32_bf16 v[106:109], v[164:167], v[204:207], v[106:109]
	v_mfma_f32_16x16x32_bf16 v[94:97], v[156:159], v[212:215], v[94:97]
	v_mfma_f32_16x16x32_bf16 v[90:93], v[164:167], v[212:215], v[90:93]
	v_mfma_f32_16x16x32_bf16 v[78:81], v[156:159], v[220:223], v[78:81]
	v_mfma_f32_16x16x32_bf16 v[74:77], v[164:167], v[220:223], v[74:77]
	v_mfma_f32_16x16x32_bf16 v[118:121], v[168:171], v[192:195], v[118:121]
	v_mfma_f32_16x16x32_bf16 v[114:117], v[184:187], v[192:195], v[114:117]
	v_mfma_f32_16x16x32_bf16 v[102:105], v[168:171], v[200:203], v[102:105]
	v_mfma_f32_16x16x32_bf16 v[98:101], v[184:187], v[200:203], v[98:101]
	v_mfma_f32_16x16x32_bf16 v[86:89], v[168:171], v[208:211], v[86:89]
	v_mfma_f32_16x16x32_bf16 v[82:85], v[184:187], v[208:211], v[82:85]
	v_mfma_f32_16x16x32_bf16 v[70:73], v[168:171], v[216:219], v[70:73]
	v_mfma_f32_16x16x32_bf16 v[66:69], v[184:187], v[216:219], v[66:69]
	v_mfma_f32_16x16x32_bf16 v[118:121], v[172:175], v[196:199], v[118:121]
	v_mfma_f32_16x16x32_bf16 v[114:117], v[188:191], v[196:199], v[114:117]
	v_mfma_f32_16x16x32_bf16 v[102:105], v[172:175], v[204:207], v[102:105]
	v_mfma_f32_16x16x32_bf16 v[98:101], v[188:191], v[204:207], v[98:101]
	v_mfma_f32_16x16x32_bf16 v[86:89], v[172:175], v[212:215], v[86:89]
	v_mfma_f32_16x16x32_bf16 v[82:85], v[188:191], v[212:215], v[82:85]
	v_mfma_f32_16x16x32_bf16 v[70:73], v[172:175], v[220:223], v[70:73]
	v_mfma_f32_16x16x32_bf16 v[66:69], v[188:191], v[220:223], v[66:69]
	s_barrier
	s_add_i32 s99, s99, s14
	v_lshl_add_u64 v[178:179], s[50:51], 0, v[0:1]
	s_mov_b32 m0, s99
	ds_read_b128 v[192:195], v149 offset:16384
	ds_read_b128 v[196:199], v149 offset:17408
	ds_read_b128 v[200:203], v149 offset:18432
	ds_read_b128 v[204:207], v149 offset:19456
	ds_read_b128 v[208:211], v149 offset:20480
	ds_read_b128 v[212:215], v149 offset:21504
	ds_read_b128 v[216:219], v149 offset:22528
	ds_read_b128 v[220:223], v149 offset:23552
	global_load_lds_dwordx4 v[178:179], off
	s_add_i32 m0, s99, 0x2000
	v_lshl_add_u64 v[224:225], s[50:51], 0, v[138:139]
	s_add_u32 s50, s50, s54
	s_addc_u32 s51, s51, 0
	s_add_i32 s99, vcc_lo, s14
	global_load_lds_dwordx4 v[224:225], off
	v_lshl_add_u64 v[226:227], s[50:51], 0, v[0:1]
	s_mov_b32 m0, s99
	v_lshl_add_u64 v[228:229], s[50:51], 0, v[138:139]
	global_load_lds_dwordx4 v[226:227], off
	s_add_i32 m0, s99, 0x2000
	v_lshl_add_u64 v[230:231], s[34:35], 0, v[134:135]
	global_load_lds_dwordx4 v[228:229], off
	s_mov_b32 m0, s11
	v_lshl_add_u64 v[232:233], s[34:35], 0, v[136:137]
	global_load_lds_dwordx4 v[230:231], off
	s_mov_b32 m0, s24
	s_nop 0
	global_load_lds_dwordx4 v[232:233], off
	s_waitcnt vmcnt(8)
	s_waitcnt lgkmcnt(0)
	s_barrier
	s_waitcnt lgkmcnt(0)
	v_mfma_f32_16x16x32_bf16 v[62:65], v[130:133], v[192:195], v[62:65]
	v_mfma_f32_16x16x32_bf16 v[58:61], v[160:163], v[192:195], v[58:61]
	v_mfma_f32_16x16x32_bf16 v[46:49], v[130:133], v[200:203], v[46:49]
	v_mfma_f32_16x16x32_bf16 v[42:45], v[160:163], v[200:203], v[42:45]
	v_mfma_f32_16x16x32_bf16 v[30:33], v[130:133], v[208:211], v[30:33]
	v_mfma_f32_16x16x32_bf16 v[26:29], v[160:163], v[208:211], v[26:29]
	v_mfma_f32_16x16x32_bf16 v[14:17], v[130:133], v[216:219], v[14:17]
	v_mfma_f32_16x16x32_bf16 v[10:13], v[160:163], v[216:219], v[10:13]
	v_mfma_f32_16x16x32_bf16 v[62:65], v[156:159], v[196:199], v[62:65]
	v_mfma_f32_16x16x32_bf16 v[58:61], v[164:167], v[196:199], v[58:61]
	v_mfma_f32_16x16x32_bf16 v[46:49], v[156:159], v[204:207], v[46:49]
	v_mfma_f32_16x16x32_bf16 v[42:45], v[164:167], v[204:207], v[42:45]
	v_mfma_f32_16x16x32_bf16 v[30:33], v[156:159], v[212:215], v[30:33]
	v_mfma_f32_16x16x32_bf16 v[26:29], v[164:167], v[212:215], v[26:29]
	v_mfma_f32_16x16x32_bf16 v[14:17], v[156:159], v[220:223], v[14:17]
	v_mfma_f32_16x16x32_bf16 v[10:13], v[164:167], v[220:223], v[10:13]
	v_mfma_f32_16x16x32_bf16 v[54:57], v[168:171], v[192:195], v[54:57]
	v_mfma_f32_16x16x32_bf16 v[50:53], v[184:187], v[192:195], v[50:53]
	v_mfma_f32_16x16x32_bf16 v[38:41], v[168:171], v[200:203], v[38:41]
	v_mfma_f32_16x16x32_bf16 v[34:37], v[184:187], v[200:203], v[34:37]
	v_mfma_f32_16x16x32_bf16 v[22:25], v[168:171], v[208:211], v[22:25]
	v_mfma_f32_16x16x32_bf16 v[18:21], v[184:187], v[208:211], v[18:21]
	v_mfma_f32_16x16x32_bf16 v[6:9], v[168:171], v[216:219], v[6:9]
	v_mfma_f32_16x16x32_bf16 v[2:5], v[184:187], v[216:219], v[2:5]
	v_mfma_f32_16x16x32_bf16 v[54:57], v[172:175], v[196:199], v[54:57]
	v_mfma_f32_16x16x32_bf16 v[50:53], v[188:191], v[196:199], v[50:53]
	v_mfma_f32_16x16x32_bf16 v[38:41], v[172:175], v[204:207], v[38:41]
	v_mfma_f32_16x16x32_bf16 v[34:37], v[188:191], v[204:207], v[34:37]
	v_mfma_f32_16x16x32_bf16 v[22:25], v[172:175], v[212:215], v[22:25]
	v_mfma_f32_16x16x32_bf16 v[18:21], v[188:191], v[212:215], v[18:21]
	v_mfma_f32_16x16x32_bf16 v[6:9], v[172:175], v[220:223], v[6:9]
	v_mfma_f32_16x16x32_bf16 v[2:5], v[188:191], v[220:223], v[2:5]
	s_barrier
	s_add_i32 s50, 0, 0x18000
	s_add_i32 s51, 0, 0x1c000
	v_add_u32_e32 v164, s50, v143
	v_add_u32_e32 v188, s51, v143
	ds_read_b128 v[130:133], v164
	ds_read_b128 v[156:159], v164 offset:1024
	ds_read_b128 v[160:163], v164 offset:2048
	ds_read_b128 v[164:167], v164 offset:3072
	ds_read_b128 v[168:171], v188
	ds_read_b128 v[172:175], v188 offset:1024
	ds_read_b128 v[184:187], v188 offset:2048
	ds_read_b128 v[188:191], v188 offset:3072
	s_add_u32 s34, s34, s54
	s_addc_u32 s35, s35, 0
	s_mov_b32 m0, s25
	v_lshl_add_u64 v[234:235], s[34:35], 0, v[134:135]
	ds_read_b128 v[192:195], v149 offset:32768
	ds_read_b128 v[196:199], v149 offset:33792
	ds_read_b128 v[200:203], v149 offset:34816
	ds_read_b128 v[204:207], v149 offset:35840
	ds_read_b128 v[208:211], v149 offset:36864
	ds_read_b128 v[212:215], v149 offset:37888
	ds_read_b128 v[216:219], v149 offset:38912
	ds_read_b128 v[220:223], v149 offset:39936
	global_load_lds_dwordx4 v[234:235], off
	v_lshl_add_u64 v[234:235], s[34:35], 0, v[136:137]
	s_mov_b32 m0, s28
	s_nop 0
	global_load_lds_dwordx4 v[234:235], off
	s_waitcnt vmcnt(8)
	s_waitcnt lgkmcnt(0)
	s_barrier
	s_waitcnt lgkmcnt(0)
	v_mfma_f32_16x16x32_bf16 v[126:129], v[130:133], v[192:195], v[126:129]
	v_mfma_f32_16x16x32_bf16 v[122:125], v[160:163], v[192:195], v[122:125]
	v_mfma_f32_16x16x32_bf16 v[110:113], v[130:133], v[200:203], v[110:113]
	v_mfma_f32_16x16x32_bf16 v[106:109], v[160:163], v[200:203], v[106:109]
	v_mfma_f32_16x16x32_bf16 v[94:97], v[130:133], v[208:211], v[94:97]
	v_mfma_f32_16x16x32_bf16 v[90:93], v[160:163], v[208:211], v[90:93]
	v_mfma_f32_16x16x32_bf16 v[78:81], v[130:133], v[216:219], v[78:81]
	v_mfma_f32_16x16x32_bf16 v[74:77], v[160:163], v[216:219], v[74:77]
	v_mfma_f32_16x16x32_bf16 v[126:129], v[156:159], v[196:199], v[126:129]
	v_mfma_f32_16x16x32_bf16 v[122:125], v[164:167], v[196:199], v[122:125]
	v_mfma_f32_16x16x32_bf16 v[110:113], v[156:159], v[204:207], v[110:113]
	v_mfma_f32_16x16x32_bf16 v[106:109], v[164:167], v[204:207], v[106:109]
	v_mfma_f32_16x16x32_bf16 v[94:97], v[156:159], v[212:215], v[94:97]
	v_mfma_f32_16x16x32_bf16 v[90:93], v[164:167], v[212:215], v[90:93]
	v_mfma_f32_16x16x32_bf16 v[78:81], v[156:159], v[220:223], v[78:81]
	v_mfma_f32_16x16x32_bf16 v[74:77], v[164:167], v[220:223], v[74:77]
	v_mfma_f32_16x16x32_bf16 v[118:121], v[168:171], v[192:195], v[118:121]
	v_mfma_f32_16x16x32_bf16 v[114:117], v[184:187], v[192:195], v[114:117]
	v_mfma_f32_16x16x32_bf16 v[102:105], v[168:171], v[200:203], v[102:105]
	v_mfma_f32_16x16x32_bf16 v[98:101], v[184:187], v[200:203], v[98:101]
	v_mfma_f32_16x16x32_bf16 v[86:89], v[168:171], v[208:211], v[86:89]
	v_mfma_f32_16x16x32_bf16 v[82:85], v[184:187], v[208:211], v[82:85]
	v_mfma_f32_16x16x32_bf16 v[70:73], v[168:171], v[216:219], v[70:73]
	v_mfma_f32_16x16x32_bf16 v[66:69], v[184:187], v[216:219], v[66:69]
	v_mfma_f32_16x16x32_bf16 v[118:121], v[172:175], v[196:199], v[118:121]
	v_mfma_f32_16x16x32_bf16 v[114:117], v[188:191], v[196:199], v[114:117]
	v_mfma_f32_16x16x32_bf16 v[102:105], v[172:175], v[204:207], v[102:105]
	v_mfma_f32_16x16x32_bf16 v[98:101], v[188:191], v[204:207], v[98:101]
	v_mfma_f32_16x16x32_bf16 v[86:89], v[172:175], v[212:215], v[86:89]
	v_mfma_f32_16x16x32_bf16 v[82:85], v[188:191], v[212:215], v[82:85]
	v_mfma_f32_16x16x32_bf16 v[70:73], v[172:175], v[220:223], v[70:73]
	v_mfma_f32_16x16x32_bf16 v[66:69], v[188:191], v[220:223], v[66:69]
	s_barrier
	s_add_i32 s34, s50, s14
	v_lshl_add_u64 v[178:179], v[178:179], 0, s[56:57]
	s_mov_b32 m0, s34
	ds_read_b128 v[192:195], v149 offset:49152
	ds_read_b128 v[196:199], v149 offset:50176
	ds_read_b128 v[200:203], v149 offset:51200
	ds_read_b128 v[204:207], v149 offset:52224
	ds_read_b128 v[208:211], v149 offset:53248
	ds_read_b128 v[212:215], v149 offset:54272
	ds_read_b128 v[216:219], v149 offset:55296
	ds_read_b128 v[220:223], v149 offset:56320
	global_load_lds_dwordx4 v[178:179], off
	v_lshl_add_u64 v[178:179], v[224:225], 0, s[56:57]
	s_add_i32 m0, s34, 0x2000
	s_add_i32 s34, s51, s14
	global_load_lds_dwordx4 v[178:179], off
	v_lshl_add_u64 v[178:179], v[226:227], 0, s[56:57]
	s_mov_b32 m0, s34
	s_nop 0
	global_load_lds_dwordx4 v[178:179], off
	v_lshl_add_u64 v[178:179], v[228:229], 0, s[56:57]
	s_add_i32 m0, s34, 0x2000
	s_nop 0
	global_load_lds_dwordx4 v[178:179], off
	v_lshl_add_u64 v[178:179], v[230:231], 0, s[56:57]
	s_mov_b32 m0, s63
	s_nop 0
	global_load_lds_dwordx4 v[178:179], off
	v_lshl_add_u64 v[178:179], v[232:233], 0, s[56:57]
	s_mov_b32 m0, s4
	s_nop 0
	global_load_lds_dwordx4 v[178:179], off
	s_waitcnt vmcnt(8)
	s_waitcnt lgkmcnt(0)
	s_barrier
	s_waitcnt lgkmcnt(0)
	v_mfma_f32_16x16x32_bf16 v[62:65], v[130:133], v[192:195], v[62:65]
	v_mfma_f32_16x16x32_bf16 v[58:61], v[160:163], v[192:195], v[58:61]
	v_mfma_f32_16x16x32_bf16 v[46:49], v[130:133], v[200:203], v[46:49]
	v_mfma_f32_16x16x32_bf16 v[42:45], v[160:163], v[200:203], v[42:45]
	v_mfma_f32_16x16x32_bf16 v[30:33], v[130:133], v[208:211], v[30:33]
	v_mfma_f32_16x16x32_bf16 v[26:29], v[160:163], v[208:211], v[26:29]
	v_mfma_f32_16x16x32_bf16 v[14:17], v[130:133], v[216:219], v[14:17]
	v_mfma_f32_16x16x32_bf16 v[10:13], v[160:163], v[216:219], v[10:13]
	v_mfma_f32_16x16x32_bf16 v[62:65], v[156:159], v[196:199], v[62:65]
	v_mfma_f32_16x16x32_bf16 v[58:61], v[164:167], v[196:199], v[58:61]
	v_mfma_f32_16x16x32_bf16 v[46:49], v[156:159], v[204:207], v[46:49]
	v_mfma_f32_16x16x32_bf16 v[42:45], v[164:167], v[204:207], v[42:45]
	v_mfma_f32_16x16x32_bf16 v[30:33], v[156:159], v[212:215], v[30:33]
	v_mfma_f32_16x16x32_bf16 v[26:29], v[164:167], v[212:215], v[26:29]
	v_mfma_f32_16x16x32_bf16 v[14:17], v[156:159], v[220:223], v[14:17]
	v_mfma_f32_16x16x32_bf16 v[10:13], v[164:167], v[220:223], v[10:13]
	v_mfma_f32_16x16x32_bf16 v[54:57], v[168:171], v[192:195], v[54:57]
	v_mfma_f32_16x16x32_bf16 v[50:53], v[184:187], v[192:195], v[50:53]
	v_mfma_f32_16x16x32_bf16 v[38:41], v[168:171], v[200:203], v[38:41]
	v_mfma_f32_16x16x32_bf16 v[34:37], v[184:187], v[200:203], v[34:37]
	v_mfma_f32_16x16x32_bf16 v[22:25], v[168:171], v[208:211], v[22:25]
	v_mfma_f32_16x16x32_bf16 v[18:21], v[184:187], v[208:211], v[18:21]
	v_mfma_f32_16x16x32_bf16 v[6:9], v[168:171], v[216:219], v[6:9]
	v_mfma_f32_16x16x32_bf16 v[2:5], v[184:187], v[216:219], v[2:5]
	v_mfma_f32_16x16x32_bf16 v[54:57], v[172:175], v[196:199], v[54:57]
	v_mfma_f32_16x16x32_bf16 v[50:53], v[188:191], v[196:199], v[50:53]
	v_mfma_f32_16x16x32_bf16 v[38:41], v[172:175], v[204:207], v[38:41]
	v_mfma_f32_16x16x32_bf16 v[34:37], v[188:191], v[204:207], v[34:37]
	v_mfma_f32_16x16x32_bf16 v[22:25], v[172:175], v[212:215], v[22:25]
	v_mfma_f32_16x16x32_bf16 v[18:21], v[188:191], v[212:215], v[18:21]
	v_mfma_f32_16x16x32_bf16 v[6:9], v[172:175], v[220:223], v[6:9]
	v_mfma_f32_16x16x32_bf16 v[2:5], v[188:191], v[220:223], v[2:5]
	s_barrier
	s_add_u32 s8, s8, 0x100
	s_addc_u32 s9, s9, 0
	s_add_u32 s42, s42, 0x100
	s_addc_u32 s73, s73, 0
	s_cmp_ge_u32 s98, s29
	s_mov_b32 s34, s98
	s_cbranch_scc0 .LBB0_77
	s_and_b64 vcc, exec, s[22:23]
	s_cbranch_vccz .LBB0_80
	s_barrier
